# combo3g + rope epilogues (ph1, ph10): 8-byte store pairs merged to 16-byte stores via v_permlane16_swap
# speedup vs baseline: 1.0217x; 1.0107x over previous
; __device__ __forceinline__ unsigned cvt_pk_bf16(float lo, float hi) { unsigned r; asm volatile("v_cvt_pk_bf16_f32 %0, %1, %2" : "=v"(r) : "v"(lo), "v"(hi)); return r; }
;     __device__ __forceinline__ void operator()(const pg8::f32x4 (&acc)[2][2][4][2], const Unit& u, int wr, int wc, int fr, int fq) const {
;     ...
;         if (pn < rope_tiles) {
;             const float s_ = (pn >= sc_lo && pn < sc_hi) ? sc : 1.f;
;             const int i0 = 16 * (wc & 1) + 4 * fq;
;             f32x4 cN = *(const f32x4*)(cs + (row0 & (SEQL - 1)) * 64 + i0), sN = *(const f32x4*)(cs + (row0 & (SEQL - 1)) * 64 + 32 + i0);
; #pragma unroll
;             for (int k = 0; k < 8; ++k) { const int ai = k >> 2, m = k & 3; const int row = row0 + ai * HALF + m * 16; const float s = s_ * rsv[k];
;                 const f32x4 c = cN, sn = sN;
;                 if (k < 7) { const int rown = row0 + ((k + 1) >> 2) * HALF + ((k + 1) & 3) * 16, posn = rown & (SEQL - 1); cN = *(const f32x4*)(cs + posn * 64 + i0); sN = *(const f32x4*)(cs + posn * 64 + 32 + i0); }
; #pragma unroll
;                 for (int bj = 0; bj < 2; ++bj) { const f32x4 x1 = acc[ai][bj][m][0], x2 = acc[ai][bj][m][1];
;                     const f32x4 o1 = (x1 * c - x2 * sn) * s, o2 = (x2 * c + x1 * sn) * s;
;                     bf16* p = Ob + (size_t)row * ldc + pt * BM + bj * HALF + 64 * (wc >> 1) + i0;
;                     v2u w1, w2; w1.x = cvt_pk_bf16(o1[0], o1[1]); w1.y = cvt_pk_bf16(o1[2], o1[3]); w2.x = cvt_pk_bf16(o2[0], o2[1]); w2.y = cvt_pk_bf16(o2[2], o2[3]);
;                     *(v2u*)p = w1; *(v2u*)(p + 32) = w2; } }
.LBB0_208:
	v_lshlrev_b32_e32 v138, 8, v178
	v_and_b32_e32 v138, 0xfcf00, v138
	v_lshl_add_u64 v[184:185], s[10:11], 0, v[138:139]
	v_lshlrev_b32_e32 v138, 2, v140
	v_lshl_add_u64 v[200:201], v[184:185], 0, v[138:139]
	v_add_co_u32_e32 v192, vcc, s58, v200
	global_load_dwordx4 v[184:187], v[200:201], off offset:128
	global_load_dwordx4 v[188:191], v[200:201], off
	v_addc_co_u32_e32 v193, vcc, 0, v201, vcc
	v_add_co_u32_e32 v202, vcc, s44, v200
	global_load_dwordx4 v[192:195], v[192:193], off offset:128
	s_nop 0
	v_addc_co_u32_e32 v203, vcc, 0, v201, vcc
	global_load_dwordx4 v[196:199], v[202:203], off offset:-4096
	s_cmp_gt_i32 s0, 1
	s_cselect_b64 vcc, -1, 0
	s_lshl_b32 s4, s4, 28
	s_lshl_b32 s0, s0, 8
	s_sub_i32 s4, s0, s4
	s_ashr_i32 s5, s4, 31
	s_lshl_b64 s[4:5], s[4:5], 1
	s_add_u32 s0, s1, s4
	s_addc_u32 s1, s2, s5
	s_add_u32 s0, s0, s57
	v_lshlrev_b32_e32 v204, 1, v140
	v_mov_b32_e32 v205, v139
	s_addc_u32 s1, s1, 0
	v_lshlrev_b64 v[206:207], 12, v[176:177]
	v_lshl_add_u64 v[176:177], s[0:1], 0, v[204:205]
	v_mbcnt_lo_u32_b32 v250, -1, 0
	v_mbcnt_hi_u32_b32 v250, -1, v250
	v_bfe_u32 v250, v250, 4, 1
	v_mul_u32_u24_e32 v250, 56, v250
	v_mov_b32_e32 v251, 0
	v_lshl_add_u64 v[176:177], v[176:177], 0, v[250:251]
	v_cndmask_b32_e32 v155, 1.0, v183, vcc
	v_lshl_add_u64 v[204:205], v[176:177], 0, v[206:207]
	v_lshlrev_b64 v[178:179], 12, v[178:179]
	v_mul_f32_e32 v180, v155, v180
	v_lshl_add_u64 v[178:179], v[176:177], 0, v[178:179]
	v_mul_f32_e32 v182, v155, v182
	v_add_co_u32_e32 v200, vcc, s59, v200
	s_waitcnt vmcnt(3)
	v_pk_mul_f32 v[206:207], v[124:125], v[186:187]
	v_pk_mul_f32 v[208:209], v[122:123], v[184:185]
	v_pk_mul_f32 v[210:211], v[128:129], v[186:187]
	v_pk_mul_f32 v[212:213], v[126:127], v[184:185]
	v_pk_mul_f32 v[214:215], v[116:117], v[186:187]
	v_pk_mul_f32 v[216:217], v[114:115], v[184:185]
	v_pk_mul_f32 v[186:187], v[120:121], v[186:187]
	v_pk_mul_f32 v[184:185], v[118:119], v[184:185]
	s_waitcnt vmcnt(2)
	v_pk_fma_f32 v[128:129], v[128:129], v[190:191], v[206:207] neg_lo:[0,0,1] neg_hi:[0,0,1]
	v_pk_fma_f32 v[126:127], v[126:127], v[188:189], v[208:209] neg_lo:[0,0,1] neg_hi:[0,0,1]
	v_pk_fma_f32 v[124:125], v[124:125], v[190:191], v[210:211]
	v_pk_fma_f32 v[122:123], v[122:123], v[188:189], v[212:213]
	v_pk_fma_f32 v[120:121], v[120:121], v[190:191], v[214:215] neg_lo:[0,0,1] neg_hi:[0,0,1]
	v_pk_fma_f32 v[118:119], v[118:119], v[188:189], v[216:217] neg_lo:[0,0,1] neg_hi:[0,0,1]
	v_pk_fma_f32 v[116:117], v[116:117], v[190:191], v[186:187]
	v_pk_fma_f32 v[114:115], v[114:115], v[188:189], v[184:185]
	s_waitcnt vmcnt(1)
	v_pk_mul_f32 v[184:185], v[108:109], v[194:195]
	v_pk_mul_f32 v[188:189], v[112:113], v[194:195]
	v_pk_mul_f32 v[128:129], v[180:181], v[128:129] op_sel_hi:[0,1]
	v_pk_mul_f32 v[126:127], v[180:181], v[126:127] op_sel_hi:[0,1]
	v_pk_mul_f32 v[124:125], v[180:181], v[124:125] op_sel_hi:[0,1]
	v_pk_mul_f32 v[122:123], v[180:181], v[122:123] op_sel_hi:[0,1]
	v_pk_mul_f32 v[120:121], v[180:181], v[120:121] op_sel_hi:[0,1]
	v_pk_mul_f32 v[118:119], v[180:181], v[118:119] op_sel_hi:[0,1]
	v_pk_mul_f32 v[116:117], v[180:181], v[116:117] op_sel_hi:[0,1]
	v_pk_mul_f32 v[114:115], v[180:181], v[114:115] op_sel_hi:[0,1]
	s_waitcnt vmcnt(0)
	v_pk_fma_f32 v[180:181], v[112:113], v[198:199], v[184:185] neg_lo:[0,0,1] neg_hi:[0,0,1]
	v_cvt_pk_bf16_f32 v246, v126, v127
	v_cvt_pk_bf16_f32 v247, v128, v129
	v_pk_mul_f32 v[186:187], v[106:107], v[192:193]
	v_cvt_pk_bf16_f32 v248, v122, v123
	v_cvt_pk_bf16_f32 v249, v124, v125
	s_nop 1
	v_permlane16_swap_b32 v246, v248
	v_permlane16_swap_b32 v247, v249
	global_store_dwordx4 v[178:179], v[246:249], off
	v_cvt_pk_bf16_f32 v250, v118, v119
	v_cvt_pk_bf16_f32 v251, v120, v121
	v_pk_mul_f32 v[190:191], v[110:111], v[192:193]
	v_pk_mul_f32 v[208:209], v[98:99], v[192:193]
	v_cvt_pk_bf16_f32 v252, v114, v115
	v_cvt_pk_bf16_f32 v253, v116, v117
	s_nop 1
	v_permlane16_swap_b32 v250, v252
	v_permlane16_swap_b32 v251, v253
	global_store_dwordx4 v[178:179], v[250:253], off offset:256
	v_pk_fma_f32 v[110:111], v[110:111], v[196:197], v[186:187] neg_lo:[0,0,1] neg_hi:[0,0,1]
	v_pk_mul_f32 v[206:207], v[100:101], v[194:195]
	v_pk_mul_f32 v[192:193], v[102:103], v[192:193]
	global_load_dwordx4 v[112:115], v[202:203], off
	global_load_dwordx4 v[116:119], v[202:203], off offset:128
	v_pk_fma_f32 v[106:107], v[106:107], v[196:197], v[190:191]
	v_pk_fma_f32 v[102:103], v[102:103], v[196:197], v[208:209] neg_lo:[0,0,1] neg_hi:[0,0,1]
	v_pk_mul_f32 v[110:111], v[182:183], v[110:111] op_sel_hi:[0,1]
	v_pk_mul_f32 v[194:195], v[104:105], v[194:195]
	v_pk_fma_f32 v[108:109], v[108:109], v[198:199], v[188:189]
	v_pk_fma_f32 v[104:105], v[104:105], v[198:199], v[206:207] neg_lo:[0,0,1] neg_hi:[0,0,1]
	v_pk_fma_f32 v[98:99], v[98:99], v[196:197], v[192:193]
	v_pk_mul_f32 v[120:121], v[182:183], v[180:181] op_sel_hi:[0,1]
	v_pk_mul_f32 v[106:107], v[182:183], v[106:107] op_sel_hi:[0,1]
	v_pk_mul_f32 v[102:103], v[182:183], v[102:103] op_sel_hi:[0,1]
	v_cvt_pk_bf16_f32 v246, v110, v111
	v_cvt_pk_bf16_f32 v247, v120, v121
	v_pk_fma_f32 v[100:101], v[100:101], v[198:199], v[194:195]
	v_pk_mul_f32 v[108:109], v[182:183], v[108:109] op_sel_hi:[0,1]
	v_pk_mul_f32 v[104:105], v[182:183], v[104:105] op_sel_hi:[0,1]
	v_pk_mul_f32 v[98:99], v[182:183], v[98:99] op_sel_hi:[0,1]
	v_cvt_pk_bf16_f32 v248, v106, v107
	v_cvt_pk_bf16_f32 v249, v108, v109
	s_nop 1
	v_permlane16_swap_b32 v246, v248
	v_permlane16_swap_b32 v247, v249
	global_store_dwordx4 v[204:205], v[246:249], off
	v_cvt_pk_bf16_f32 v250, v102, v103
	v_cvt_pk_bf16_f32 v251, v104, v105
	v_addc_co_u32_e32 v201, vcc, 0, v201, vcc
	v_pk_mul_f32 v[100:101], v[182:183], v[100:101] op_sel_hi:[0,1]
	v_cvt_pk_bf16_f32 v252, v98, v99
	v_cvt_pk_bf16_f32 v253, v100, v101
	s_nop 1
	v_permlane16_swap_b32 v250, v252
	v_permlane16_swap_b32 v251, v253
	global_store_dwordx4 v[204:205], v[250:253], off offset:256
	global_load_dwordx4 v[100:103], v[200:201], off offset:128
	s_nop 0
	global_load_dwordx4 v[104:107], v[200:201], off
	v_lshlrev_b64 v[110:111], 12, v[168:169]
	v_lshlrev_b64 v[108:109], 12, v[170:171]
	v_mul_f32_e32 v120, v155, v172
	v_lshlrev_b32_e32 v98, 8, v158
	v_mov_b32_e32 v99, v139
	v_and_b32_e32 v98, 0xfcf00, v98
	v_lshl_add_u64 v[108:109], v[176:177], 0, v[108:109]
	v_mul_f32_e32 v122, v155, v174
	v_lshl_add_u64 v[98:99], s[10:11], 0, v[98:99]
	v_lshl_add_u64 v[98:99], v[98:99], 0, v[138:139]
	v_lshl_add_u64 v[110:111], v[176:177], 0, v[110:111]
	s_waitcnt vmcnt(4)
; __device__ __forceinline__ unsigned cvt_pk_bf16(float lo, float hi) { unsigned r; asm volatile("v_cvt_pk_bf16_f32 %0, %1, %2" : "=v"(r) : "v"(lo), "v"(hi)); return r; }
;     __device__ __forceinline__ void operator()(const pg8::f32x4 (&acc)[2][2][4][2], const Unit& u, int wr, int wc, int fr, int fq) const {
;     ...
;         if (pn < rope_tiles) {
;             const float s_ = (pn >= sc_lo && pn < sc_hi) ? sc : 1.f;
;             const int i0 = 16 * (wc & 1) + 4 * fq;
;             f32x4 cN = *(const f32x4*)(cs + (row0 & (SEQL - 1)) * 64 + i0), sN = *(const f32x4*)(cs + (row0 & (SEQL - 1)) * 64 + 32 + i0);
; #pragma unroll
;             for (int k = 0; k < 8; ++k) { const int ai = k >> 2, m = k & 3; const int row = row0 + ai * HALF + m * 16; const float s = s_ * rsv[k];
;                 const f32x4 c = cN, sn = sN;
;                 if (k < 7) { const int rown = row0 + ((k + 1) >> 2) * HALF + ((k + 1) & 3) * 16, posn = rown & (SEQL - 1); cN = *(const f32x4*)(cs + posn * 64 + i0); sN = *(const f32x4*)(cs + posn * 64 + 32 + i0); }
; #pragma unroll
;                 for (int bj = 0; bj < 2; ++bj) { const f32x4 x1 = acc[ai][bj][m][0], x2 = acc[ai][bj][m][1];
;                     const f32x4 o1 = (x1 * c - x2 * sn) * s, o2 = (x2 * c + x1 * sn) * s;
;                     bf16* p = Ob + (size_t)row * ldc + pt * BM + bj * HALF + 64 * (wc >> 1) + i0;
;                     v2u w1, w2; w1.x = cvt_pk_bf16(o1[0], o1[1]); w1.y = cvt_pk_bf16(o1[2], o1[3]); w2.x = cvt_pk_bf16(o2[0], o2[1]); w2.y = cvt_pk_bf16(o2[2], o2[3]);
;                     *(v2u*)p = w1; *(v2u*)(p + 32) = w2; } }
	v_pk_mul_f32 v[124:125], v[92:93], v[118:119]
	v_pk_mul_f32 v[126:127], v[90:91], v[116:117]
	v_pk_mul_f32 v[128:129], v[96:97], v[118:119]
	v_pk_mul_f32 v[168:169], v[94:95], v[116:117]
	v_pk_mul_f32 v[170:171], v[84:85], v[118:119]
	v_pk_mul_f32 v[178:179], v[82:83], v[116:117]
	v_pk_mul_f32 v[118:119], v[88:89], v[118:119]
	v_pk_mul_f32 v[116:117], v[86:87], v[116:117]
	v_pk_fma_f32 v[96:97], v[96:97], v[114:115], v[124:125] neg_lo:[0,0,1] neg_hi:[0,0,1]
	v_pk_fma_f32 v[94:95], v[94:95], v[112:113], v[126:127] neg_lo:[0,0,1] neg_hi:[0,0,1]
	v_pk_fma_f32 v[92:93], v[92:93], v[114:115], v[128:129]
	v_pk_fma_f32 v[90:91], v[90:91], v[112:113], v[168:169]
	v_pk_fma_f32 v[86:87], v[86:87], v[112:113], v[178:179] neg_lo:[0,0,1] neg_hi:[0,0,1]
	v_pk_fma_f32 v[84:85], v[84:85], v[114:115], v[118:119]
	v_pk_fma_f32 v[82:83], v[82:83], v[112:113], v[116:117]
	v_pk_mul_f32 v[96:97], v[120:121], v[96:97] op_sel_hi:[0,1]
	v_pk_mul_f32 v[94:95], v[120:121], v[94:95] op_sel_hi:[0,1]
	v_pk_mul_f32 v[92:93], v[120:121], v[92:93] op_sel_hi:[0,1]
	v_pk_mul_f32 v[90:91], v[120:121], v[90:91] op_sel_hi:[0,1]
	v_pk_fma_f32 v[88:89], v[88:89], v[114:115], v[170:171] neg_lo:[0,0,1] neg_hi:[0,0,1]
	v_pk_mul_f32 v[86:87], v[120:121], v[86:87] op_sel_hi:[0,1]
	v_pk_mul_f32 v[84:85], v[120:121], v[84:85] op_sel_hi:[0,1]
	v_pk_mul_f32 v[82:83], v[120:121], v[82:83] op_sel_hi:[0,1]
	v_cvt_pk_bf16_f32 v246, v94, v95
	v_cvt_pk_bf16_f32 v247, v96, v97
	v_cvt_pk_bf16_f32 v248, v90, v91
	v_cvt_pk_bf16_f32 v249, v92, v93
	s_waitcnt vmcnt(1)
	v_pk_mul_f32 v[92:93], v[76:77], v[102:103]
	v_pk_mul_f32 v[96:97], v[74:75], v[100:101]
	v_pk_mul_f32 v[112:113], v[80:81], v[102:103]
	v_pk_mul_f32 v[88:89], v[120:121], v[88:89] op_sel_hi:[0,1]
	v_pk_mul_f32 v[114:115], v[78:79], v[100:101]
	s_nop 1
	v_permlane16_swap_b32 v246, v248
	v_permlane16_swap_b32 v247, v249
	global_store_dwordx4 v[108:109], v[246:249], off
	v_cvt_pk_bf16_f32 v250, v86, v87
	v_cvt_pk_bf16_f32 v251, v88, v89
	v_cvt_pk_bf16_f32 v252, v82, v83
	v_cvt_pk_bf16_f32 v253, v84, v85
	s_waitcnt vmcnt(1)
	v_pk_fma_f32 v[80:81], v[80:81], v[106:107], v[92:93] neg_lo:[0,0,1] neg_hi:[0,0,1]
	v_pk_fma_f32 v[78:79], v[78:79], v[104:105], v[96:97] neg_lo:[0,0,1] neg_hi:[0,0,1]
	v_pk_fma_f32 v[84:85], v[76:77], v[106:107], v[112:113]
	v_pk_fma_f32 v[88:89], v[74:75], v[104:105], v[114:115]
	s_nop 1
	v_permlane16_swap_b32 v250, v252
	v_permlane16_swap_b32 v251, v253
	global_store_dwordx4 v[108:109], v[250:253], off offset:256
	v_pk_mul_f32 v[82:83], v[122:123], v[80:81] op_sel_hi:[0,1]
	v_pk_mul_f32 v[86:87], v[122:123], v[78:79] op_sel_hi:[0,1]
	v_pk_mul_f32 v[84:85], v[122:123], v[84:85] op_sel_hi:[0,1]
	global_load_dwordx4 v[74:77], v[98:99], off
	global_load_dwordx4 v[78:81], v[98:99], off offset:128
	v_pk_mul_f32 v[88:89], v[122:123], v[88:89] op_sel_hi:[0,1]
	v_cvt_pk_bf16_f32 v246, v86, v87
	v_cvt_pk_bf16_f32 v247, v82, v83
	v_cvt_pk_bf16_f32 v248, v88, v89
	v_cvt_pk_bf16_f32 v249, v84, v85
	v_pk_mul_f32 v[84:85], v[66:67], v[100:101]
	s_nop 1
	v_permlane16_swap_b32 v246, v248
	v_permlane16_swap_b32 v247, v249
	global_store_dwordx4 v[110:111], v[246:249], off
	v_pk_fma_f32 v[84:85], v[70:71], v[104:105], v[84:85] neg_lo:[0,0,1] neg_hi:[0,0,1]
	v_pk_mul_f32 v[70:71], v[70:71], v[100:101]
	v_pk_mul_f32 v[82:83], v[68:69], v[102:103]
	v_pk_fma_f32 v[66:67], v[66:67], v[104:105], v[70:71]
	v_pk_fma_f32 v[82:83], v[72:73], v[106:107], v[82:83] neg_lo:[0,0,1] neg_hi:[0,0,1]
	v_pk_mul_f32 v[72:73], v[72:73], v[102:103]
	v_pk_mul_f32 v[66:67], v[122:123], v[66:67] op_sel_hi:[0,1]
	v_pk_mul_f32 v[82:83], v[122:123], v[82:83] op_sel_hi:[0,1]
	v_pk_mul_f32 v[84:85], v[122:123], v[84:85] op_sel_hi:[0,1]
	v_pk_fma_f32 v[68:69], v[68:69], v[106:107], v[72:73]
	v_cvt_pk_bf16_f32 v250, v84, v85
	v_cvt_pk_bf16_f32 v251, v82, v83
	v_cvt_pk_bf16_f32 v252, v66, v67
	v_mul_f32_e32 v88, v155, v164
	v_pk_mul_f32 v[68:69], v[122:123], v[68:69] op_sel_hi:[0,1]
	v_cvt_pk_bf16_f32 v253, v68, v69
	s_nop 1
	v_permlane16_swap_b32 v250, v252
	v_permlane16_swap_b32 v251, v253
	global_store_dwordx4 v[110:111], v[250:253], off offset:256
	v_add_co_u32_e32 v66, vcc, s58, v98
	v_lshlrev_b64 v[84:85], 12, v[158:159]
	s_nop 0
	v_addc_co_u32_e32 v67, vcc, 0, v99, vcc
	v_add_co_u32_e32 v82, vcc, s44, v98
	global_load_dwordx4 v[66:69], v[66:67], off offset:128
	s_nop 0
	v_addc_co_u32_e32 v83, vcc, 0, v99, vcc
	global_load_dwordx4 v[70:73], v[82:83], off offset:-4096
	v_lshl_add_u64 v[84:85], v[176:177], 0, v[84:85]
	v_or_b32_e32 v86, 16, v158
	v_ashrrev_i32_e32 v87, 31, v86
	v_mul_f32_e32 v90, v155, v166
	v_lshlrev_b64 v[86:87], 12, v[86:87]
	v_lshl_add_u64 v[86:87], v[176:177], 0, v[86:87]
	s_waitcnt vmcnt(4)
	v_pk_mul_f32 v[92:93], v[60:61], v[80:81]
	v_pk_mul_f32 v[94:95], v[58:59], v[78:79]
	v_pk_mul_f32 v[96:97], v[64:65], v[80:81]
	v_pk_mul_f32 v[100:101], v[62:63], v[78:79]
	v_pk_fma_f32 v[64:65], v[64:65], v[76:77], v[92:93] neg_lo:[0,0,1] neg_hi:[0,0,1]
	v_pk_fma_f32 v[62:63], v[62:63], v[74:75], v[94:95] neg_lo:[0,0,1] neg_hi:[0,0,1]
	v_pk_fma_f32 v[60:61], v[60:61], v[76:77], v[96:97]
	v_pk_fma_f32 v[58:59], v[58:59], v[74:75], v[100:101]
	v_pk_mul_f32 v[104:105], v[50:51], v[78:79]
	v_pk_mul_f32 v[64:65], v[88:89], v[64:65] op_sel_hi:[0,1]
	v_pk_mul_f32 v[62:63], v[88:89], v[62:63] op_sel_hi:[0,1]
	v_pk_mul_f32 v[60:61], v[88:89], v[60:61] op_sel_hi:[0,1]
	v_pk_mul_f32 v[58:59], v[88:89], v[58:59] op_sel_hi:[0,1]
	v_pk_mul_f32 v[102:103], v[52:53], v[80:81]
	v_pk_mul_f32 v[78:79], v[54:55], v[78:79]
	v_pk_fma_f32 v[54:55], v[54:55], v[74:75], v[104:105] neg_lo:[0,0,1] neg_hi:[0,0,1]
	v_cvt_pk_bf16_f32 v246, v62, v63
	v_cvt_pk_bf16_f32 v247, v64, v65
	v_cvt_pk_bf16_f32 v248, v58, v59
	v_cvt_pk_bf16_f32 v249, v60, v61
	v_pk_mul_f32 v[80:81], v[56:57], v[80:81]
	v_pk_fma_f32 v[56:57], v[56:57], v[76:77], v[102:103] neg_lo:[0,0,1] neg_hi:[0,0,1]
	v_pk_fma_f32 v[50:51], v[50:51], v[74:75], v[78:79]
	v_pk_mul_f32 v[54:55], v[88:89], v[54:55] op_sel_hi:[0,1]
	s_nop 1
	v_permlane16_swap_b32 v246, v248
	v_permlane16_swap_b32 v247, v249
	global_store_dwordx4 v[84:85], v[246:249], off
	v_pk_fma_f32 v[52:53], v[52:53], v[76:77], v[80:81]
	v_pk_mul_f32 v[56:57], v[88:89], v[56:57] op_sel_hi:[0,1]
	v_pk_mul_f32 v[50:51], v[88:89], v[50:51] op_sel_hi:[0,1]
	v_cvt_pk_bf16_f32 v250, v54, v55
	v_cvt_pk_bf16_f32 v251, v56, v57
	v_pk_mul_f32 v[52:53], v[88:89], v[52:53] op_sel_hi:[0,1]
	v_cvt_pk_bf16_f32 v252, v50, v51
	s_waitcnt vmcnt(2)
; __device__ __forceinline__ unsigned cvt_pk_bf16(float lo, float hi) { unsigned r; asm volatile("v_cvt_pk_bf16_f32 %0, %1, %2" : "=v"(r) : "v"(lo), "v"(hi)); return r; }
;     __device__ __forceinline__ void operator()(const pg8::f32x4 (&acc)[2][2][4][2], const Unit& u, int wr, int wc, int fr, int fq) const {
;     ...
;         if (pn < rope_tiles) {
;             const float s_ = (pn >= sc_lo && pn < sc_hi) ? sc : 1.f;
;             const int i0 = 16 * (wc & 1) + 4 * fq;
;             f32x4 cN = *(const f32x4*)(cs + (row0 & (SEQL - 1)) * 64 + i0), sN = *(const f32x4*)(cs + (row0 & (SEQL - 1)) * 64 + 32 + i0);
; #pragma unroll
;             for (int k = 0; k < 8; ++k) { const int ai = k >> 2, m = k & 3; const int row = row0 + ai * HALF + m * 16; const float s = s_ * rsv[k];
;                 const f32x4 c = cN, sn = sN;
;                 if (k < 7) { const int rown = row0 + ((k + 1) >> 2) * HALF + ((k + 1) & 3) * 16, posn = rown & (SEQL - 1); cN = *(const f32x4*)(cs + posn * 64 + i0); sN = *(const f32x4*)(cs + posn * 64 + 32 + i0); }
; #pragma unroll
;                 for (int bj = 0; bj < 2; ++bj) { const f32x4 x1 = acc[ai][bj][m][0], x2 = acc[ai][bj][m][1];
;                     const f32x4 o1 = (x1 * c - x2 * sn) * s, o2 = (x2 * c + x1 * sn) * s;
;                     bf16* p = Ob + (size_t)row * ldc + pt * BM + bj * HALF + 64 * (wc >> 1) + i0;
;                     v2u w1, w2; w1.x = cvt_pk_bf16(o1[0], o1[1]); w1.y = cvt_pk_bf16(o1[2], o1[3]); w2.x = cvt_pk_bf16(o2[0], o2[1]); w2.y = cvt_pk_bf16(o2[2], o2[3]);
;                     *(v2u*)p = w1; *(v2u*)(p + 32) = w2; } }
	v_pk_mul_f32 v[60:61], v[44:45], v[68:69]
	v_pk_mul_f32 v[64:65], v[42:43], v[66:67]
	v_cvt_pk_bf16_f32 v253, v52, v53
	s_waitcnt vmcnt(1)
	v_pk_fma_f32 v[58:59], v[48:49], v[72:73], v[60:61] neg_lo:[0,0,1] neg_hi:[0,0,1]
	v_pk_fma_f32 v[60:61], v[46:47], v[70:71], v[64:65] neg_lo:[0,0,1] neg_hi:[0,0,1]
	v_pk_mul_f32 v[48:49], v[48:49], v[68:69]
	v_pk_mul_f32 v[46:47], v[46:47], v[66:67]
	v_pk_fma_f32 v[44:45], v[44:45], v[72:73], v[48:49]
	v_pk_fma_f32 v[42:43], v[42:43], v[70:71], v[46:47]
	s_nop 1
	v_permlane16_swap_b32 v250, v252
	v_permlane16_swap_b32 v251, v253
	global_store_dwordx4 v[84:85], v[250:253], off offset:256
	v_pk_mul_f32 v[44:45], v[90:91], v[44:45] op_sel_hi:[0,1]
	v_pk_mul_f32 v[42:43], v[90:91], v[42:43] op_sel_hi:[0,1]
	global_load_dwordx4 v[50:53], v[82:83], off
	global_load_dwordx4 v[54:57], v[82:83], off offset:128
	v_pk_mul_f32 v[58:59], v[90:91], v[58:59] op_sel_hi:[0,1]
	v_pk_mul_f32 v[60:61], v[90:91], v[60:61] op_sel_hi:[0,1]
	v_cvt_pk_bf16_f32 v246, v60, v61
	v_cvt_pk_bf16_f32 v247, v58, v59
	v_cvt_pk_bf16_f32 v248, v42, v43
	v_cvt_pk_bf16_f32 v249, v44, v45
	v_pk_mul_f32 v[44:45], v[34:35], v[66:67]
	s_nop 1
	v_permlane16_swap_b32 v246, v248
	v_permlane16_swap_b32 v247, v249
	global_store_dwordx4 v[86:87], v[246:249], off
	v_pk_mul_f32 v[42:43], v[36:37], v[68:69]
	v_pk_fma_f32 v[44:45], v[38:39], v[70:71], v[44:45] neg_lo:[0,0,1] neg_hi:[0,0,1]
	v_pk_mul_f32 v[38:39], v[38:39], v[66:67]
	v_pk_fma_f32 v[42:43], v[40:41], v[72:73], v[42:43] neg_lo:[0,0,1] neg_hi:[0,0,1]
	v_pk_mul_f32 v[40:41], v[40:41], v[68:69]
	v_pk_fma_f32 v[34:35], v[34:35], v[70:71], v[38:39]
	v_pk_mul_f32 v[42:43], v[90:91], v[42:43] op_sel_hi:[0,1]
	v_pk_mul_f32 v[44:45], v[90:91], v[44:45] op_sel_hi:[0,1]
	v_pk_fma_f32 v[36:37], v[36:37], v[72:73], v[40:41]
	v_pk_mul_f32 v[34:35], v[90:91], v[34:35] op_sel_hi:[0,1]
	v_cvt_pk_bf16_f32 v250, v44, v45
	v_cvt_pk_bf16_f32 v251, v42, v43
	v_pk_mul_f32 v[36:37], v[90:91], v[36:37] op_sel_hi:[0,1]
	v_cvt_pk_bf16_f32 v252, v34, v35
	v_cvt_pk_bf16_f32 v253, v36, v37
	s_nop 1
	v_permlane16_swap_b32 v250, v252
	v_permlane16_swap_b32 v251, v253
	global_store_dwordx4 v[86:87], v[250:253], off offset:256
	v_add_co_u32_e32 v38, vcc, s59, v98
	v_or_b32_e32 v42, 32, v158
	s_nop 0
	v_addc_co_u32_e32 v39, vcc, 0, v99, vcc
	global_load_dwordx4 v[34:37], v[38:39], off offset:128
	s_nop 0
	global_load_dwordx4 v[38:41], v[38:39], off
	v_ashrrev_i32_e32 v43, 31, v42
	v_mul_f32_e32 v46, v155, v160
	v_lshlrev_b64 v[42:43], 12, v[42:43]
	v_lshl_add_u64 v[42:43], v[176:177], 0, v[42:43]
	v_or_b32_e32 v44, 48, v158
	v_ashrrev_i32_e32 v45, 31, v44
	v_mul_f32_e32 v48, v155, v162
	v_lshlrev_b64 v[44:45], 12, v[44:45]
	v_lshl_add_u64 v[44:45], v[176:177], 0, v[44:45]
	s_waitcnt vmcnt(4)
	v_pk_mul_f32 v[60:61], v[26:27], v[54:55]
	v_pk_mul_f32 v[58:59], v[28:29], v[56:57]
	v_pk_mul_f32 v[64:65], v[30:31], v[54:55]
	v_pk_mul_f32 v[68:69], v[18:19], v[54:55]
	v_pk_mul_f32 v[54:55], v[22:23], v[54:55]
	v_pk_fma_f32 v[30:31], v[30:31], v[50:51], v[60:61] neg_lo:[0,0,1] neg_hi:[0,0,1]
	v_pk_mul_f32 v[62:63], v[32:33], v[56:57]
	v_pk_mul_f32 v[66:67], v[20:21], v[56:57]
	v_pk_mul_f32 v[56:57], v[24:25], v[56:57]
	v_pk_fma_f32 v[32:33], v[32:33], v[52:53], v[58:59] neg_lo:[0,0,1] neg_hi:[0,0,1]
	v_pk_fma_f32 v[26:27], v[26:27], v[50:51], v[64:65]
	v_pk_fma_f32 v[22:23], v[22:23], v[50:51], v[68:69] neg_lo:[0,0,1] neg_hi:[0,0,1]
	v_pk_fma_f32 v[18:19], v[18:19], v[50:51], v[54:55]
	v_pk_mul_f32 v[30:31], v[46:47], v[30:31] op_sel_hi:[0,1]
	v_pk_fma_f32 v[28:29], v[28:29], v[52:53], v[62:63]
	v_pk_fma_f32 v[24:25], v[24:25], v[52:53], v[66:67] neg_lo:[0,0,1] neg_hi:[0,0,1]
	v_pk_fma_f32 v[20:21], v[20:21], v[52:53], v[56:57]
	v_pk_mul_f32 v[32:33], v[46:47], v[32:33] op_sel_hi:[0,1]
	v_pk_mul_f32 v[26:27], v[46:47], v[26:27] op_sel_hi:[0,1]
	v_pk_mul_f32 v[22:23], v[46:47], v[22:23] op_sel_hi:[0,1]
	v_pk_mul_f32 v[18:19], v[46:47], v[18:19] op_sel_hi:[0,1]
	v_cvt_pk_bf16_f32 v246, v30, v31
	v_cvt_pk_bf16_f32 v247, v32, v33
	v_pk_mul_f32 v[28:29], v[46:47], v[28:29] op_sel_hi:[0,1]
	v_pk_mul_f32 v[24:25], v[46:47], v[24:25] op_sel_hi:[0,1]
	v_pk_mul_f32 v[20:21], v[46:47], v[20:21] op_sel_hi:[0,1]
	v_cvt_pk_bf16_f32 v248, v26, v27
	v_cvt_pk_bf16_f32 v249, v28, v29
	s_nop 1
	v_permlane16_swap_b32 v246, v248
	v_permlane16_swap_b32 v247, v249
	global_store_dwordx4 v[42:43], v[246:249], off
	v_cvt_pk_bf16_f32 v250, v22, v23
	v_cvt_pk_bf16_f32 v251, v24, v25
	v_cvt_pk_bf16_f32 v252, v18, v19
	v_cvt_pk_bf16_f32 v253, v20, v21
	s_waitcnt vmcnt(2)
	v_pk_mul_f32 v[28:29], v[12:13], v[36:37]
	s_nop 1
	v_permlane16_swap_b32 v250, v252
	v_permlane16_swap_b32 v251, v253
	global_store_dwordx4 v[42:43], v[250:253], off offset:256
	v_pk_mul_f32 v[18:19], v[10:11], v[34:35]
	s_waitcnt vmcnt(2)
	v_pk_fma_f32 v[20:21], v[16:17], v[40:41], v[28:29] neg_lo:[0,0,1] neg_hi:[0,0,1]
	v_pk_fma_f32 v[18:19], v[14:15], v[38:39], v[18:19] neg_lo:[0,0,1] neg_hi:[0,0,1]
	v_pk_mul_f32 v[16:17], v[16:17], v[36:37]
	v_pk_mul_f32 v[14:15], v[14:15], v[34:35]
	v_pk_fma_f32 v[12:13], v[12:13], v[40:41], v[16:17]
	v_pk_fma_f32 v[10:11], v[10:11], v[38:39], v[14:15]
	v_pk_mul_f32 v[12:13], v[48:49], v[12:13] op_sel_hi:[0,1]
	v_pk_mul_f32 v[10:11], v[48:49], v[10:11] op_sel_hi:[0,1]
	v_pk_mul_f32 v[20:21], v[48:49], v[20:21] op_sel_hi:[0,1]
	v_pk_mul_f32 v[18:19], v[48:49], v[18:19] op_sel_hi:[0,1]
	v_cvt_pk_bf16_f32 v246, v18, v19
	v_cvt_pk_bf16_f32 v247, v20, v21
	v_cvt_pk_bf16_f32 v248, v10, v11
	v_cvt_pk_bf16_f32 v249, v12, v13
	v_pk_mul_f32 v[12:13], v[2:3], v[34:35]
	s_nop 1
	v_permlane16_swap_b32 v246, v248
	v_permlane16_swap_b32 v247, v249
	global_store_dwordx4 v[44:45], v[246:249], off
	v_pk_mul_f32 v[10:11], v[4:5], v[36:37]
	v_pk_fma_f32 v[12:13], v[6:7], v[38:39], v[12:13] neg_lo:[0,0,1] neg_hi:[0,0,1]
	v_pk_mul_f32 v[6:7], v[6:7], v[34:35]
	v_pk_fma_f32 v[10:11], v[8:9], v[40:41], v[10:11] neg_lo:[0,0,1] neg_hi:[0,0,1]
	v_pk_mul_f32 v[8:9], v[8:9], v[36:37]
	v_pk_fma_f32 v[2:3], v[2:3], v[38:39], v[6:7]
	v_pk_mul_f32 v[10:11], v[48:49], v[10:11] op_sel_hi:[0,1]
	v_pk_mul_f32 v[12:13], v[48:49], v[12:13] op_sel_hi:[0,1]
	v_pk_fma_f32 v[4:5], v[4:5], v[40:41], v[8:9]
	v_pk_mul_f32 v[2:3], v[48:49], v[2:3] op_sel_hi:[0,1]
	v_cvt_pk_bf16_f32 v250, v12, v13
	v_cvt_pk_bf16_f32 v251, v10, v11
	v_pk_mul_f32 v[4:5], v[48:49], v[4:5] op_sel_hi:[0,1]
	v_cvt_pk_bf16_f32 v252, v2, v3
	v_cvt_pk_bf16_f32 v253, v4, v5
	s_nop 1
	v_permlane16_swap_b32 v250, v252
	v_permlane16_swap_b32 v251, v253
	global_store_dwordx4 v[44:45], v[250:253], off offset:256
	s_andn2_b64 vcc, exec, s[6:7]
	s_mov_b64 s[4:5], -1
	s_cbranch_vccnz .LBB0_193
